# selected stream tile loop: per-stage 4-bit work mask walked with s_ff1 (skipped tiles free, shorter per-tile scalar prologue, ANYM reload at stage head); on top of v33
# speedup vs baseline: 1.0134x; 1.0134x over previous
; #define LAS __attribute__((address_space(3)))
; __device__ __forceinline__ int launder_v(int x) { asm volatile("" : "+v"(x)); return x; }
; __device__ __forceinline__ int launder_s(int x) { x = __builtin_amdgcn_readfirstlane(x); asm volatile("" : "+s"(x)); return x; }
; template <int STG, class F>
; __device__ __forceinline__ void stream_tiles(Ctx& C, const TileSrc& src, int tile0, int ntiles, LAS unsigned char* bufs, F&& compute) {
;     ...
;     const int nst = (ntiles + STG - 1) / STG, tlast = tile0 + ntiles - 1;
;     v4u rk[STG], rv[STG];
;     { const int tidl = launder_v(C.tid);
; #pragma unroll
;       for (int h = 0; h < STG; ++h) { const int t = tile0 + h; tile_fetch(src, 64 * (t < tlast ? t : tlast), tidl, rk[h], rv[h]); }
; #pragma unroll
;       for (int h = 0; h < STG; ++h) tile_store(bufs + h * 16384, tidl, rk[h], rv[h]); }
;     __syncthreads();
; __device__ __forceinline__ void nsa_block_task(Ctx& C, int task, bf16* ONSA_OUT) {
;     ...
; #pragma unroll
;         for (int cg = 0; cg < 2; ++cg)
; #pragma unroll
;             for (int c = 0; c < 4; ++c) oc[cg][c] = o[cg][c] * g_c[cg];
;     }
;     WAVE_SYNC();
;     {
; #pragma unroll 1
;         for (int q = 0; q < 8; ++q) {
;             if (qb < 16) { if (lane < 8) SELM[q * 8 + lane] = (lane == 0) ? ((1u << (qb + 1)) - 1u) : 0u; }
;             else select_blocks(SC + q * 256, SELM + q * 8, qb - 2, qb, qb - 1, lane);
;         }
;     }
;     WAVE_SYNC();
;     LAS unsigned* ANYM = (LAS unsigned*)(C.lds + 135168 + w * 64);
;     { const int la = launder_v(lane); if (la < 16) { const int cgx = la >> 3, w8 = la & 7; ANYM[la] = SELM[(4 * cgx + 0) * 8 + w8] | SELM[(4 * cgx + 1) * 8 + w8] | SELM[(4 * cgx + 2) * 8 + w8] | SELM[(4 * cgx + 3) * 8 + w8]; } }
;     WAVE_SYNC();
;     f4* STASH = WSP(f4, WS_STASH) + (size_t)(C.bid * NWAVES + w) * 512;
; #pragma unroll
;     for (int cg = 0; cg < 2; ++cg)
; #pragma unroll
;         for (int c = 0; c < 4; ++c) STASH[(cg * 4 + c) * 64 + lane] = oc[cg][c];
;     __syncthreads();
;     {
;         AttnAcc a[2]; attn_init(a[0]); attn_init(a[1]);
;         const int kvs = launder_s(kvh);
;         const TileSrc src{WSP(bf16, WS_KS) + (size_t)kvs * RP * 64, WSP(bf16, WS_VST) + (size_t)kvs * 64 * RP, RP};
;         int cw = -1; unsigned aw0 = 0u, aw1 = 0u;
;         stream_tiles<4>(C, src, 0, qb, bufs, [&](const LAS unsigned char* buf, int j) {
.LBB0_1206:
	s_or_b64 exec, exec, s[16:17]
	v_pk_mul_f32 v[32:33], v[186:187], v[32:33] op_sel_hi:[0,1]
	v_pk_mul_f32 v[34:35], v[186:187], v[34:35] op_sel_hi:[0,1]
	s_mov_b32 s3, s97
	v_pk_mul_f32 v[48:49], v[186:187], v[48:49] op_sel_hi:[0,1]
	v_pk_mul_f32 v[50:51], v[186:187], v[50:51] op_sel_hi:[0,1]
	v_pk_mul_f32 v[44:45], v[186:187], v[44:45] op_sel_hi:[0,1]
	v_pk_mul_f32 v[46:47], v[186:187], v[46:47] op_sel_hi:[0,1]
	v_pk_mul_f32 v[36:37], v[182:183], v[36:37] op_sel_hi:[0,1]
	v_pk_mul_f32 v[38:39], v[182:183], v[38:39] op_sel_hi:[0,1]
	v_pk_mul_f32 v[40:41], v[182:183], v[40:41] op_sel_hi:[0,1]
	v_pk_mul_f32 v[42:43], v[182:183], v[42:43] op_sel_hi:[0,1]
	v_pk_mul_f32 v[28:29], v[186:187], v[28:29] op_sel_hi:[0,1]
	v_pk_mul_f32 v[30:31], v[186:187], v[30:31] op_sel_hi:[0,1]
	v_pk_mul_f32 v[20:21], v[182:183], v[20:21] op_sel_hi:[0,1]
	v_pk_mul_f32 v[22:23], v[182:183], v[22:23] op_sel_hi:[0,1]
	v_pk_mul_f32 v[24:25], v[182:183], v[24:25] op_sel_hi:[0,1]
	v_pk_mul_f32 v[26:27], v[182:183], v[26:27] op_sel_hi:[0,1]
	s_waitcnt lgkmcnt(0)
	v_mov_b64_e32 v[176:177], v[32:33]
	v_mov_b64_e32 v[178:179], v[34:35]
	v_mov_b64_e32 v[180:181], v[48:49]
	v_mov_b64_e32 v[204:205], v[50:51]
	v_mov_b64_e32 v[206:207], v[28:29]
	v_mov_b64_e32 v[208:209], v[30:31]
	v_mov_b64_e32 v[234:235], v[44:45]
	v_mov_b64_e32 v[236:237], v[46:47]
	v_mov_b64_e32 v[238:239], v[20:21]
	v_mov_b64_e32 v[240:241], v[22:23]
	v_mov_b64_e32 v[242:243], v[36:37]
	v_mov_b64_e32 v[244:245], v[38:39]
	v_mov_b64_e32 v[246:247], v[24:25]
	v_mov_b64_e32 v[248:249], v[26:27]
	v_mov_b64_e32 v[250:251], v[40:41]
	v_mov_b64_e32 v[252:253], v[42:43]
	s_waitcnt lgkmcnt(0)
	s_barrier
	s_mul_hi_i32 s17, s3, 0x208000
	s_mul_i32 s3, s3, 0x208000
	s_add_u32 s18, s79, s3
	s_addc_u32 s19, s80, s17
	s_add_u32 s16, s81, s3
	s_addc_u32 s17, s82, s17
	s_cmp_eq_u32 s94, 0
	s_mov_b32 s26, 0
	s_cbranch_scc1 .LBB0_1229
	v_mov_b32_e32 v36, v189
	s_add_i32 s3, s94, 3
	v_ashrrev_i32_e32 v20, 3, v36
	v_lshlrev_b32_e32 v28, 4, v36
	v_and_b32_e32 v0, 0x70, v28
	v_ashrrev_i32_e32 v21, 31, v20
	v_mov_b64_e32 v[22:23], s[16:17]
	v_lshl_add_u64 v[2:3], s[18:19], 0, v[0:1]
	v_mad_i64_i32 v[22:23], s[20:21], v20, s92, v[22:23]
	v_lshlrev_b64 v[24:25], 7, v[20:21]
	s_cmp_eq_u32 s0, 0
	v_lshl_add_u64 v[24:25], v[2:3], 0, v[24:25]
	s_cselect_b32 s20, 0, 64
	v_lshl_add_u64 v[22:23], v[22:23], 0, v[0:1]
	v_add_u32_e32 v24, s20, v20
	v_ashrrev_i32_e32 v25, 31, v24
	v_lshlrev_b64 v[24:25], 7, v[24:25]
	v_lshl_add_u64 v[24:25], v[2:3], 0, v[24:25]
	s_lshl_b32 s50, s20, 1
	s_min_u32 s20, s0, 2
	v_lshl_add_u64 v[26:27], v[22:23], 0, s[50:51]
	v_lshl_add_u32 v24, s20, 6, v20
	v_ashrrev_i32_e32 v25, 31, v24
	v_lshlrev_b64 v[24:25], 7, v[24:25]
	v_lshl_add_u64 v[24:25], v[2:3], 0, v[24:25]
	s_lshl_b32 s50, s20, 7
	s_min_u32 s20, s0, 3
	v_lshl_add_u64 v[26:27], v[22:23], 0, s[50:51]
	v_lshl_add_u32 v24, s20, 6, v20
	v_ashrrev_i32_e32 v25, 31, v24
	v_lshlrev_b64 v[24:25], 7, v[24:25]
	v_lshl_add_u64 v[2:3], v[2:3], 0, v[24:25]
	s_lshl_b32 s50, s20, 7
	v_lshl_add_u64 v[22:23], v[22:23], 0, s[50:51]
	v_lshrrev_b32_e32 v233, 3, v189
	v_and_b32_e32 v254, 7, v189
	v_bfe_u32 v174, v233, 1, 3
	v_xor_b32_e32 v254, v254, v174
	v_lshlrev_b32_e32 v254, 4, v254
	v_mul_lo_u32 v198, v233, s92
	v_add_u32_e32 v198, v198, v254
	v_and_b32_e32 v174, 32, v233
	v_bfe_u32 v175, v233, 2, 2
	v_lshl_or_b32 v174, v175, 3, v174
	v_bfe_u32 v175, v233, 4, 1
	v_lshl_or_b32 v174, v175, 2, v174
	v_and_or_b32 v174, v233, 3, v174
	v_lshl_add_u32 v185, v174, 7, v254
	v_readfirstlane_b32 s44, v189
	s_lshl_b32 s44, s44, 4
	s_mov_b32 s28, 0
	s_mov_b32 s3, 0
	s_add_i32 s45, s3, s44
	s_min_i32 s24, s28, s0
	s_add_i32 m0, s45, 0x0
	s_lshl_b32 s98, s24, 13
	s_add_u32 s98, s18, s98
	s_addc_u32 s99, s19, 0
	global_load_lds_dwordx4 v185, s[98:99]
	s_add_i32 m0, s45, 0x2000
	s_lshl_b32 s100, s24, 7
	s_add_u32 s100, s16, s100
	s_addc_u32 s101, s17, 0
	global_load_lds_dwordx4 v198, s[100:101]
	s_add_i32 s24, s28, 1
	s_min_i32 s24, s24, s0
	s_add_i32 m0, s45, 0x4000
	s_lshl_b32 s98, s24, 13
	s_add_u32 s98, s18, s98
	s_addc_u32 s99, s19, 0
	global_load_lds_dwordx4 v185, s[98:99]
	s_add_i32 m0, s45, 0x6000
	s_lshl_b32 s100, s24, 7
	s_add_u32 s100, s16, s100
	s_addc_u32 s101, s17, 0
	global_load_lds_dwordx4 v198, s[100:101]
	s_add_i32 s24, s28, 2
	s_min_i32 s24, s24, s0
	s_add_i32 m0, s45, 0x8000
	s_lshl_b32 s98, s24, 13
	s_add_u32 s98, s18, s98
	s_addc_u32 s99, s19, 0
	global_load_lds_dwordx4 v185, s[98:99]
	s_add_i32 m0, s45, 0xa000
	s_lshl_b32 s100, s24, 7
	s_add_u32 s100, s16, s100
	s_addc_u32 s101, s17, 0
	global_load_lds_dwordx4 v198, s[100:101]
	s_add_i32 s24, s28, 3
	s_min_i32 s24, s24, s0
	s_add_i32 m0, s45, 0xc000
	s_lshl_b32 s98, s24, 13
	s_add_u32 s98, s18, s98
	s_addc_u32 s99, s19, 0
	global_load_lds_dwordx4 v185, s[98:99]
	s_add_i32 m0, s45, 0xe000
	s_lshl_b32 s100, s24, 7
	s_add_u32 s100, s16, s100
	s_addc_u32 s101, s17, 0
	global_load_lds_dwordx4 v198, s[100:101]
	s_add_i32 s3, s94, 3
	v_lshlrev_b32_e32 v0, 2, v20
	v_lshrrev_b32_e32 v21, 1, v20
	v_mov_b32_e32 v2, v1
	v_mov_b32_e32 v3, v1
	v_and_b32_e32 v22, 35, v20
	v_lshlrev_b32_e32 v20, 7, v20
	v_bitop3_b32 v23, v28, s91, v36 bitop3:0x48
	v_and_b32_e32 v24, 16, v0
	v_and_b32_e32 v21, 12, v21
	v_add3_u32 v37, 0, v20, v23
	v_mov_b32_e32 v0, v1
	v_or3_b32 v38, v24, v22, v21
	v_mov_b64_e32 v[22:23], v[2:3]
	v_mov_b64_e32 v[26:27], v[2:3]
	v_mov_b64_e32 v[30:31], v[2:3]
	v_mov_b64_e32 v[34:35], v[2:3]
	v_mov_b64_e32 v[42:43], v[2:3]
	v_mov_b64_e32 v[46:47], v[2:3]
	v_mov_b64_e32 v[50:51], v[2:3]
	v_mov_b64_e32 v[54:55], v[2:3]
	v_mov_b64_e32 v[20:21], v[0:1]
	v_mov_b64_e32 v[24:25], v[0:1]
	v_mov_b64_e32 v[28:29], v[0:1]
	v_mov_b64_e32 v[32:33], v[0:1]
	v_mov_b64_e32 v[40:41], v[0:1]
	v_mov_b64_e32 v[44:45], v[0:1]
	v_mov_b64_e32 v[48:49], v[0:1]
	v_mov_b64_e32 v[52:53], v[0:1]
	v_lshrrev_b32_e32 v2, 1, v38
	v_xor_b32_e32 v2, v2, v36
	v_lshlrev_b32_e32 v2, 4, v2
	v_lshlrev_b32_e32 v0, 7, v38
	v_and_b32_e32 v2, 0x70, v2
	s_mov_b32 s27, 0
	v_mov_b32_e32 v169, 0xc4800000
	v_mov_b32_e32 v168, 0
	s_mov_b32 s22, -1
	s_mov_b32 s49, -1
	s_mov_b32 s28, 0
	s_mov_b32 s31, 0
	s_mov_b32 s30, 0
	s_lshr_b32 s29, s3, 2
	v_add3_u32 v0, 0, v0, v2
	v_mov_b32_e32 v36, 0
	v_mov_b32_e32 v170, 0xc4800000
	s_mov_b32 s23, 0
	v_ashrrev_i32_e32 v226, 4, v190
	v_lshrrev_b32_e32 v225, 1, v190
	v_bitop3_b32 v233, v225, v226, 7 bitop3:0x6c
	v_lshlrev_b32_e32 v254, 7, v190
	v_add_u32_e32 v226, 4, v226
	v_lshlrev_b32_e32 v233, 4, v233
	v_and_b32_e32 v254, 0x780, v254
	v_bitop3_b32 v226, v226, v225, 7 bitop3:0x78
	v_lshlrev_b32_e32 v226, 4, v226
	v_add_u32_e32 v225, v254, v233
	v_add_u32_e32 v226, v254, v226
	s_waitcnt vmcnt(0) lgkmcnt(0)
	s_waitcnt lgkmcnt(0)
	s_barrier

; #define LAS __attribute__((address_space(3)))
; template <int STG, class F>
; __device__ __forceinline__ void stream_tiles(Ctx& C, const TileSrc& src, int tile0, int ntiles, LAS unsigned char* bufs, F&& compute) {
;     ...
;         LAS unsigned char* cur = bufs + (st & 1) * (STG * 16384);
; #pragma unroll 1
;         for (int h = 0; h < STG; ++h) if (STG * st + h < ntiles) compute(cur + h * 16384, tile0 + STG * st + h);
; __device__ __forceinline__ void nsa_block_task(Ctx& C, int task, bf16* ONSA_OUT) {
;     ...
;         stream_tiles<4>(C, src, 0, qb, bufs, [&](const LAS unsigned char* buf, int j) {
;             if ((j >> 5) != cw) { cw = j >> 5; aw0 = (unsigned)__builtin_amdgcn_readfirstlane((int)ANYM[cw]); aw1 = (unsigned)__builtin_amdgcn_readfirstlane((int)ANYM[8 + cw]); }
;             bool any[2]; any[0] = (aw0 >> (j & 31)) & 1u; any[1] = (aw1 >> (j & 31)) & 1u;
;             if (any[0] || any[1]) {
.LBB0_1210:
	s_and_b32 s3, s26, 0x10000
	s_bfe_u32 s37, s23, 0x1b0003
	s_add_i32 s36, s3, 0
	s_lshl_b32 s3, s37, 2
	s_and_b32 s35, s27, 31
	s_add_i32 s38, s77, s3
	v_add_u32_e32 v171, s3, v227
	s_cmp_eq_u32 s37, s49
	s_cbranch_scc1 .Ltl_have
	v_mov_b32_e32 v0, s38
	s_waitcnt lgkmcnt(0)
	ds_read2_b32 v[2:3], v0 offset1:8
	s_waitcnt lgkmcnt(0)
	v_readfirstlane_b32 s30, v2
	v_readfirstlane_b32 s31, v3
	s_mov_b32 s49, s37
.Ltl_have:
	s_lshr_b32 s46, s30, s35
	s_lshr_b32 s47, s31, s35
	s_sub_i32 s3, s94, s28
	s_min_u32 s3, s3, 4
	s_lshl_b32 s3, 1, s3
	s_add_i32 s3, s3, -1
	s_and_b32 s46, s46, s3
	s_and_b32 s47, s47, s3
	s_or_b32 s48, s46, s47
	s_mov_b32 s41, s36
	s_branch .LBB0_1214

; #define LAS __attribute__((address_space(3)))
; __device__ __forceinline__ float fexp2(float x) { return __builtin_amdgcn_exp2f(x); }
; __device__ __forceinline__ int launder_v(int x) { asm volatile("" : "+v"(x)); return x; }
; #define MFMA16(a, b, c) __builtin_amdgcn_mfma_f32_16x16x32_bf16((a), (b), (c), 0, 0, 0)
;     f4 s[2][2];
; #pragma unroll
;     for (int ch = 0; ch < 2; ++ch)
; #pragma unroll
;         for (int kt = 0; kt < 2; ++kt) { f4 t = (f4){colbias, colbias, colbias, colbias}; t = MFMA16(kf[ch][kt][0], bq[0], t); s[ch][kt] = MFMA16(kf[ch][kt][1], bq[1], t); }
;     float mx = -1e30f;
; #pragma unroll
;     for (int ch = 0; ch < 2; ++ch)
; #pragma unroll
;         for (int h = 0; h < 2; ++h) mx = fmaxf(mx, fmaxf(fmaxf(s[ch][h][0], s[ch][h][1]), fmaxf(s[ch][h][2], s[ch][h][3])));
;     if (__any(mx > a.m + MAX_SLACK)) {
;         mx = fmaxf(mx, __shfl_xor(mx, 16)); mx = fmaxf(mx, __shfl_xor(mx, 32));
;         const float mn = fmaxf(a.m, mx), alpha = fexp2(a.m - mn); a.m = mn; a.l *= alpha;
; #pragma unroll
;         for (int c = 0; c < 4; ++c) a.o[c] = a.o[c] * alpha;
;     }
; __device__ __forceinline__ void nsa_block_task(Ctx& C, int task, bf16* ONSA_OUT) {
;     ...
;         stream_tiles<4>(C, src, 0, qb, bufs, [&](const LAS unsigned char* buf, int j) {
;             if ((j >> 5) != cw) { cw = j >> 5; aw0 = (unsigned)__builtin_amdgcn_readfirstlane((int)ANYM[cw]); aw1 = (unsigned)__builtin_amdgcn_readfirstlane((int)ANYM[8 + cw]); }
;             bool any[2]; any[0] = (aw0 >> (j & 31)) & 1u; any[1] = (aw1 >> (j & 31)) & 1u;
;             if (any[0] || any[1]) {
;                 bool mysel[2];
; #pragma unroll
;                 for (int cg = 0; cg < 2; ++cg) mysel[cg] = (SELM[(4 * cg + qi) * 8 + (j >> 5)] >> (j & 31)) & 1u;
;                 bf16x8 kf[2][2][2], vf[2][4]; { const int ll = launder_v(lane);
; #pragma unroll
;                     for (int ch = 0; ch < 2; ++ch) { tile_read_k(buf, ch, ll, kf[ch]); tile_read_v(buf, ch, ll, vf[ch]); } }
; #pragma unroll
;                 for (int cg = 0; cg < 2; ++cg) if (any[cg]) attn_tile64_full(a[cg], kf, vf, bq[cg], mysel[cg] ? 0.f : -3e30f);
.LBB0_1212:
.LBB0_1213:
.LBB0_1214:
	s_cmp_eq_u32 s48, 0
	s_cbranch_scc1 .LBB0_1225
	s_ff1_i32_b32 s39, s48
	s_bitset0_b32 s48, s39
	s_lshl_b32 s3, s39, 14
	s_add_i32 s36, s41, s3
	s_add_i32 s40, s35, s39
	s_bitcmp1_b32 s46, s39
	s_cselect_b64 s[24:25], -1, 0
	s_bitcmp1_b32 s47, s39
	s_cselect_b64 s[22:23], -1, 0
	s_waitcnt lgkmcnt(0)
	ds_read2_b32 v[2:3], v171 offset1:32
	s_andn2_b64 vcc, exec, s[24:25]
	v_add_u32_e32 v89, s36, v225
	v_add_u32_e32 v0, s36, v226
	ds_read_b128 v[140:143], v89
	ds_read_b128 v[144:147], v89 offset:2048
	ds_read_b128 v[148:151], v0
	ds_read_b128 v[128:131], v0 offset:2048
	ds_read_b128 v[136:139], v89 offset:4096
	ds_read_b128 v[124:127], v89 offset:6144
	ds_read_b128 v[132:135], v0 offset:4096
	ds_read_b128 v[120:123], v0 offset:6144
	ds_read_b128 v[116:119], v89 offset:8192
	ds_read_b128 v[112:115], v89 offset:10240
	ds_read_b128 v[108:111], v89 offset:12288
	ds_read_b128 v[104:107], v89 offset:14336
	ds_read_b128 v[96:99], v0 offset:8192
	ds_read_b128 v[100:103], v0 offset:10240
	ds_read_b128 v[92:95], v0 offset:12288
	ds_read_b128 v[88:91], v0 offset:14336
	s_cbranch_vccnz .LBB0_1222
	s_waitcnt lgkmcnt(12)
	v_bfe_i32 v0, v2, s40, 1
	v_bfi_b32 v156, v0, 0, v231
	v_sub_f32_e32 v156, v156, v170
	v_mov_b32_e32 v157, v156
	v_mov_b32_e32 v158, v156
	v_mov_b32_e32 v159, v156
	s_nop 1
	v_mfma_f32_16x16x32_bf16 v[152:155], v[140:143], v[4:7], v[156:159]
	v_mfma_f32_16x16x32_bf16 v[160:163], v[148:151], v[8:11], v[152:155]
	v_mfma_f32_16x16x32_bf16 v[152:155], v[144:147], v[4:7], v[156:159]
	v_mfma_f32_16x16x32_bf16 v[164:167], v[128:131], v[8:11], v[152:155]
	s_nop 5
	v_max3_f32 v0, v160, v161, v162
	v_max3_f32 v0, v0, v163, s93
	s_waitcnt lgkmcnt(8)
	v_mfma_f32_16x16x32_bf16 v[152:155], v[136:139], v[4:7], v[156:159]
	v_max3_f32 v0, v0, v164, v165
	v_max3_f32 v0, v0, v166, v167
	v_mfma_f32_16x16x32_bf16 v[156:159], v[124:127], v[4:7], v[156:159]
	v_mfma_f32_16x16x32_bf16 v[152:155], v[132:135], v[8:11], v[152:155]
	v_mfma_f32_16x16x32_bf16 v[156:159], v[120:123], v[8:11], v[156:159]
	s_nop 6
	v_max3_f32 v0, v0, v152, v153
	v_max3_f32 v0, v0, v154, v155
	v_max3_f32 v0, v0, v156, v157
	v_max3_f32 v0, v0, v158, v159
	v_cmp_lt_f32_e32 vcc, 0x41000000, v0
	s_cbranch_vccz .LBB0_1221
	ds_bpermute_b32 v2, v217, v0
	v_max_f32_e32 v0, v0, v0
	s_waitcnt lgkmcnt(0)
	v_max_f32_e32 v2, v2, v2
	v_max_f32_e32 v0, v0, v2
	ds_bpermute_b32 v2, v219, v0
	s_waitcnt lgkmcnt(0)
	v_max3_f32 v2, 0, v0, v2
	v_sub_f32_e32 v0, 0, v2
	v_exp_f32_e32 v0, v0
	v_add_f32_e32 v170, v170, v2
	v_sub_f32_e32 v160, v160, v2
	v_sub_f32_e32 v161, v161, v2
	v_sub_f32_e32 v162, v162, v2
	v_sub_f32_e32 v163, v163, v2
	v_sub_f32_e32 v164, v164, v2
	v_sub_f32_e32 v165, v165, v2
	v_sub_f32_e32 v166, v166, v2
	v_sub_f32_e32 v167, v167, v2
	v_sub_f32_e32 v152, v152, v2
	v_sub_f32_e32 v153, v153, v2
	v_sub_f32_e32 v154, v154, v2
	v_sub_f32_e32 v155, v155, v2
	v_sub_f32_e32 v156, v156, v2
	v_sub_f32_e32 v157, v157, v2
	v_sub_f32_e32 v158, v158, v2
	v_sub_f32_e32 v159, v159, v2
	v_mul_f32_e32 v36, v36, v0
	v_pk_mul_f32 v[54:55], v[54:55], v[0:1] op_sel_hi:[1,0]
	v_pk_mul_f32 v[52:53], v[52:53], v[0:1] op_sel_hi:[1,0]
	v_pk_mul_f32 v[50:51], v[50:51], v[0:1] op_sel_hi:[1,0]
	v_pk_mul_f32 v[48:49], v[48:49], v[0:1] op_sel_hi:[1,0]
	v_pk_mul_f32 v[46:47], v[46:47], v[0:1] op_sel_hi:[1,0]
	v_pk_mul_f32 v[44:45], v[44:45], v[0:1] op_sel_hi:[1,0]
	v_pk_mul_f32 v[42:43], v[42:43], v[0:1] op_sel_hi:[1,0]
	v_pk_mul_f32 v[40:41], v[40:41], v[0:1] op_sel_hi:[1,0]
